# NSA selected/window loops: lazy softmax rescale (threshold 44 score units) on top of v_m18
# speedup vs baseline: 1.0485x; 1.0101x over previous
.LBB0_405:
	v_max3_f32 v169, v18, v19, v20
	v_max3_f32 v171, v21, v22, v23
	v_max3_f32 v172, v24, v25, v26
	v_max3_f32 v169, v169, v27, v28
	v_max3_f32 v171, v171, v29, v30
	v_max3_f32 v172, v172, v31, v32
	v_max3_f32 v169, v169, v171, v33
	v_max_f32_e32 v169, v169, v172
	v_max3_f32 v171, v2, v3, v4
	v_max3_f32 v172, v5, v6, v7
	v_max3_f32 v173, v8, v9, v10
	v_max3_f32 v171, v171, v11, v12
	v_max3_f32 v172, v172, v13, v14
	v_max3_f32 v173, v173, v15, v16
	v_max3_f32 v171, v171, v172, v17
	v_max3_f32 v169, v169, v171, v173
	v_cndmask_b32_e64 v169, v222, v169, s[40:41]
	v_mov_b32_e32 v171, v169
	s_nop 1
	v_permlane32_swap_b32_e32 v169, v171
	v_max3_f32 v169, v170, v169, v171
	v_add_f32_e32 v171, 0x42300000, v170
	v_cmp_gt_f32_e32 vcc, v169, v171
	s_cbranch_vccz .Lmy_lazy_0
	v_sub_f32_e32 v170, v170, v169
	v_mul_f32_e32 v170, 0x3e38aa3b, v170
	v_exp_f32_e32 v170, v170
	s_nop 0
	v_mul_f32_e32 v201, v201, v170
	v_pk_mul_f32 v[80:81], v[80:81], v[170:171] op_sel_hi:[1,0]
	v_pk_mul_f32 v[78:79], v[78:79], v[170:171] op_sel_hi:[1,0]
	v_pk_mul_f32 v[76:77], v[76:77], v[170:171] op_sel_hi:[1,0]
	v_pk_mul_f32 v[74:75], v[74:75], v[170:171] op_sel_hi:[1,0]
	v_pk_mul_f32 v[72:73], v[72:73], v[170:171] op_sel_hi:[1,0]
	v_pk_mul_f32 v[70:71], v[70:71], v[170:171] op_sel_hi:[1,0]
	v_pk_mul_f32 v[68:69], v[68:69], v[170:171] op_sel_hi:[1,0]
	v_pk_mul_f32 v[66:67], v[66:67], v[170:171] op_sel_hi:[1,0]
	v_pk_mul_f32 v[96:97], v[96:97], v[170:171] op_sel_hi:[1,0]
	v_pk_mul_f32 v[94:95], v[94:95], v[170:171] op_sel_hi:[1,0]
	v_pk_mul_f32 v[92:93], v[92:93], v[170:171] op_sel_hi:[1,0]
	v_pk_mul_f32 v[90:91], v[90:91], v[170:171] op_sel_hi:[1,0]
	v_pk_mul_f32 v[88:89], v[88:89], v[170:171] op_sel_hi:[1,0]
	v_pk_mul_f32 v[86:87], v[86:87], v[170:171] op_sel_hi:[1,0]
	v_pk_mul_f32 v[84:85], v[84:85], v[170:171] op_sel_hi:[1,0]
	v_pk_mul_f32 v[82:83], v[82:83], v[170:171] op_sel_hi:[1,0]
	s_branch .LBB0_407
.Lmy_lazy_0:
	v_mov_b32_e32 v169, v170
.LBB0_407:
	v_mul_f32_e32 v170, 0xbe38aa3b, v169
	v_cndmask_b32_e64 v170, v222, v170, s[40:41]
	v_fmamk_f32 v18, v18, 0x3e38aa3b, v170
	v_fmamk_f32 v2, v2, 0x3e38aa3b, v170
	v_exp_f32_e32 v18, v18
	v_exp_f32_e32 v2, v2
	v_fmamk_f32 v19, v19, 0x3e38aa3b, v170
	v_fmamk_f32 v3, v3, 0x3e38aa3b, v170
	v_exp_f32_e32 v19, v19
	v_exp_f32_e32 v3, v3
	v_add_f32_e32 v177, v18, v2
	v_fmamk_f32 v20, v20, 0x3e38aa3b, v170
	v_fmamk_f32 v4, v4, 0x3e38aa3b, v170
	v_exp_f32_e32 v20, v20
	v_exp_f32_e32 v4, v4
	v_add_f32_e32 v176, v19, v3
	v_add_f32_e32 v177, v176, v177
	v_fmamk_f32 v21, v21, 0x3e38aa3b, v170
	v_fmamk_f32 v5, v5, 0x3e38aa3b, v170
	v_exp_f32_e32 v21, v21
	v_exp_f32_e32 v5, v5
	v_add_f32_e32 v176, v20, v4
	v_add_f32_e32 v177, v176, v177
	v_fmamk_f32 v22, v22, 0x3e38aa3b, v170
	v_fmamk_f32 v6, v6, 0x3e38aa3b, v170
	v_exp_f32_e32 v22, v22
	v_exp_f32_e32 v6, v6
	v_add_f32_e32 v176, v21, v5
	v_add_f32_e32 v177, v176, v177
	v_fmamk_f32 v23, v23, 0x3e38aa3b, v170
	v_fmamk_f32 v7, v7, 0x3e38aa3b, v170
	v_exp_f32_e32 v23, v23
	v_exp_f32_e32 v7, v7
	v_add_f32_e32 v176, v22, v6
	v_add_f32_e32 v177, v176, v177
	v_fmamk_f32 v24, v24, 0x3e38aa3b, v170
	v_fmamk_f32 v8, v8, 0x3e38aa3b, v170
	v_exp_f32_e32 v24, v24
	v_exp_f32_e32 v8, v8
	v_add_f32_e32 v176, v23, v7
	v_add_f32_e32 v177, v176, v177
	v_fmamk_f32 v25, v25, 0x3e38aa3b, v170
	v_fmamk_f32 v9, v9, 0x3e38aa3b, v170
	v_exp_f32_e32 v25, v25
	v_exp_f32_e32 v9, v9
	v_add_f32_e32 v176, v24, v8
	v_add_f32_e32 v177, v176, v177
	v_fmamk_f32 v26, v26, 0x3e38aa3b, v170
	v_fmamk_f32 v10, v10, 0x3e38aa3b, v170
	v_exp_f32_e32 v26, v26
	v_exp_f32_e32 v10, v10
	v_add_f32_e32 v176, v25, v9
	v_add_f32_e32 v177, v176, v177
	v_fmamk_f32 v27, v27, 0x3e38aa3b, v170
	v_fmamk_f32 v11, v11, 0x3e38aa3b, v170
	v_exp_f32_e32 v27, v27
	v_exp_f32_e32 v11, v11
	v_add_f32_e32 v176, v26, v10
	v_add_f32_e32 v177, v176, v177
	v_fmamk_f32 v28, v28, 0x3e38aa3b, v170
	v_fmamk_f32 v12, v12, 0x3e38aa3b, v170
	v_exp_f32_e32 v28, v28
	v_exp_f32_e32 v12, v12
	v_add_f32_e32 v176, v27, v11
	v_add_f32_e32 v177, v176, v177
	v_fmamk_f32 v29, v29, 0x3e38aa3b, v170
	v_fmamk_f32 v13, v13, 0x3e38aa3b, v170
	v_exp_f32_e32 v29, v29
	v_exp_f32_e32 v13, v13
	v_add_f32_e32 v176, v28, v12
	v_add_f32_e32 v177, v176, v177
	v_fmamk_f32 v30, v30, 0x3e38aa3b, v170
	v_fmamk_f32 v14, v14, 0x3e38aa3b, v170
	v_exp_f32_e32 v30, v30
	v_exp_f32_e32 v14, v14
	v_add_f32_e32 v176, v29, v13
	v_add_f32_e32 v177, v176, v177
	v_fmamk_f32 v31, v31, 0x3e38aa3b, v170
	v_fmamk_f32 v15, v15, 0x3e38aa3b, v170
	v_exp_f32_e32 v31, v31
	v_exp_f32_e32 v15, v15
	v_add_f32_e32 v176, v30, v14
	v_add_f32_e32 v177, v176, v177
	v_fmamk_f32 v32, v32, 0x3e38aa3b, v170
	v_fmamk_f32 v16, v16, 0x3e38aa3b, v170
	v_exp_f32_e32 v32, v32
	v_exp_f32_e32 v16, v16
	v_add_f32_e32 v176, v31, v15
	v_add_f32_e32 v177, v176, v177
	v_fmamk_f32 v33, v33, 0x3e38aa3b, v170
	v_fmamk_f32 v17, v17, 0x3e38aa3b, v170
	v_exp_f32_e32 v33, v33
	v_exp_f32_e32 v17, v17
	v_add_f32_e32 v176, v32, v16
	v_add_f32_e32 v177, v176, v177
	v_add_f32_e32 v176, v33, v17
	v_add_f32_e32 v177, v176, v177
	v_cvt_pk_bf16_f32 v172, v18, v19
	v_cvt_pk_bf16_f32 v173, v20, v21
	v_cvt_pk_bf16_f32 v174, v22, v23
	v_cvt_pk_bf16_f32 v175, v24, v25
	v_cvt_pk_bf16_f32 v9, v8, v9
	v_cvt_pk_bf16_f32 v8, v6, v7
	s_waitcnt lgkmcnt(0)
	v_mfma_f32_32x32x16_bf16 v[82:97], v[158:161], v[172:175], v[82:97]
	v_cvt_pk_bf16_f32 v7, v4, v5
	v_cvt_pk_bf16_f32 v6, v2, v3
	v_mfma_f32_32x32x16_bf16 v[66:81], v[126:129], v[172:175], v[66:81]
	v_cvt_pk_bf16_f32 v2, v10, v11
	v_cvt_pk_bf16_f32 v3, v12, v13
	v_cvt_pk_bf16_f32 v4, v14, v15
	v_cvt_pk_bf16_f32 v5, v16, v17
	v_cvt_pk_bf16_f32 v10, v26, v27
	v_cvt_pk_bf16_f32 v11, v28, v29
	v_cvt_pk_bf16_f32 v12, v30, v31
	v_cvt_pk_bf16_f32 v13, v32, v33
	v_add_f32_e32 v201, v177, v201
	s_nop 0
	v_mfma_f32_32x32x16_bf16 v[82:97], v[154:157], v[10:13], v[82:97]
	v_mfma_f32_32x32x16_bf16 v[66:81], v[122:125], v[10:13], v[66:81]
	v_mfma_f32_32x32x16_bf16 v[82:97], v[150:153], v[6:9], v[82:97]
	v_mfma_f32_32x32x16_bf16 v[66:81], v[118:121], v[6:9], v[66:81]
	v_mfma_f32_32x32x16_bf16 v[82:97], v[146:149], v[2:5], v[82:97]
	v_mfma_f32_32x32x16_bf16 v[66:81], v[114:117], v[2:5], v[66:81]
	s_xor_b32 s49, s49, 1
	s_cmp_le_i32 s1, s80
	s_cbranch_scc1 .LBB0_409
	s_branch .LBB0_410

.LBB0_416:
	v_max3_f32 v0, v114, v115, v116
	v_max3_f32 v194, v117, v118, v119
	v_max3_f32 v195, v120, v121, v122
	v_max3_f32 v0, v0, v123, v124
	v_max3_f32 v194, v194, v125, v126
	v_max3_f32 v195, v195, v127, v128
	v_max3_f32 v0, v0, v194, v129
	v_max_f32_e32 v0, v0, v195
	v_max3_f32 v194, v98, v99, v100
	v_max3_f32 v195, v101, v102, v103
	v_max3_f32 v196, v104, v105, v106
	v_max3_f32 v194, v194, v107, v108
	v_max3_f32 v195, v195, v109, v110
	v_max3_f32 v196, v196, v111, v112
	v_max3_f32 v194, v194, v195, v113
	v_max3_f32 v0, v0, v194, v196
	v_mov_b32_e32 v194, v0
	s_nop 1
	v_permlane32_swap_b32_e32 v0, v194
	v_max3_f32 v0, v242, v0, v194
	v_add_f32_e32 v194, 0x42300000, v242
	v_cmp_gt_f32_e32 vcc, v0, v194
	s_cbranch_vccz .Lmy_lazy_1
	v_sub_f32_e32 v194, v242, v0
	v_mul_f32_e32 v194, 0x3e38aa3b, v194
	v_exp_f32_e32 v194, v194
	s_nop 0
	v_mul_f32_e32 v203, v203, v194
	v_pk_mul_f32 v[32:33], v[32:33], v[194:195] op_sel_hi:[1,0]
	v_pk_mul_f32 v[30:31], v[30:31], v[194:195] op_sel_hi:[1,0]
	v_pk_mul_f32 v[28:29], v[28:29], v[194:195] op_sel_hi:[1,0]
	v_pk_mul_f32 v[26:27], v[26:27], v[194:195] op_sel_hi:[1,0]
	v_pk_mul_f32 v[24:25], v[24:25], v[194:195] op_sel_hi:[1,0]
	v_pk_mul_f32 v[22:23], v[22:23], v[194:195] op_sel_hi:[1,0]
	v_pk_mul_f32 v[20:21], v[20:21], v[194:195] op_sel_hi:[1,0]
	v_pk_mul_f32 v[18:19], v[18:19], v[194:195] op_sel_hi:[1,0]
	v_pk_mul_f32 v[16:17], v[16:17], v[194:195] op_sel_hi:[1,0]
	v_pk_mul_f32 v[14:15], v[14:15], v[194:195] op_sel_hi:[1,0]
	v_pk_mul_f32 v[12:13], v[12:13], v[194:195] op_sel_hi:[1,0]
	v_pk_mul_f32 v[10:11], v[10:11], v[194:195] op_sel_hi:[1,0]
	v_pk_mul_f32 v[8:9], v[8:9], v[194:195] op_sel_hi:[1,0]
	v_pk_mul_f32 v[6:7], v[6:7], v[194:195] op_sel_hi:[1,0]
	v_pk_mul_f32 v[4:5], v[4:5], v[194:195] op_sel_hi:[1,0]
	v_pk_mul_f32 v[2:3], v[2:3], v[194:195] op_sel_hi:[1,0]
	s_branch .LBB0_418
.Lmy_lazy_1:
	v_mov_b32_e32 v0, v242
